# code-placement A/B: whole instruction stream shifted by 4 bytes (one s_nop 0 at entry)
# baseline (speedup 1.0000x reference)
; #define LAS __attribute__((address_space(3)))
; __global__ void __launch_bounds__(512) fwd_kernel(Args a) {
;     extern __shared__ __attribute__((aligned(16))) unsigned char lds_raw[];
;     LAS unsigned char* lds = (LAS unsigned char*)lds_raw;
;     const int tid = threadIdx.x, lane = tid & 63, wave = __builtin_amdgcn_readfirstlane(tid >> 6);
;     const int G = gridDim.x, gw = blockIdx.x * 8 + wave, NGW = G * 8;
;     cg::grid_group grid = cg::this_grid();
;     volatile LAS unsigned* xst = (volatile LAS unsigned*)(lds + LDS_BYTES - 16);
;     if (tid < 4) xst[tid] = 0u;
;     __syncthreads();
;     if (a.ph_lo == 0) { if (blockIdx.x == 0) for (int i = tid; i < XCD_BAR_WORDS; i += 512) ((unsigned*)(a.ws + WS_BAR))[i] = 0u;
;         grid.sync(); (void)xcd_barrier_post((unsigned*)(a.ws + WS_BAR), xst); }
_Z10fwd_kernel4Args:
	s_nop 0
	s_load_dwordx8 s[52:59], s[0:1], 0xa0
	s_load_dwordx8 s[60:67], s[0:1], 0x80
	s_load_dword s3, s[0:1], 0xc0
	v_and_b32_e32 v178, 0x3ff, v0
	s_add_u32 s6, s0, 0xb8
	v_readfirstlane_b32 s94, v178
	s_addc_u32 s7, s1, 0
	v_cmp_gt_u32_e32 vcc, 4, v178
	s_waitcnt lgkmcnt(0)
	v_writelane_b32 v252, s3, 0
	s_and_saveexec_b64 s[4:5], vcc
	v_lshl_add_u32 v1, v178, 2, 0
	v_add_u32_e32 v1, 0x23ff0, v1
	v_mov_b32_e32 v2, 0
	ds_write_b32 v1, v2
	s_or_b64 exec, exec, s[4:5]
	s_load_dwordx16 s[8:23], s[0:1], 0x0
	s_cmp_lg_u32 s56, 0
	s_waitcnt lgkmcnt(0)
	s_barrier
	v_writelane_b32 v252, s8, 1
	s_nop 1
	v_writelane_b32 v252, s9, 2
	v_writelane_b32 v252, s10, 3
	v_writelane_b32 v252, s11, 4
	v_writelane_b32 v252, s12, 5
	v_writelane_b32 v252, s13, 6
	v_writelane_b32 v252, s14, 7
	v_writelane_b32 v252, s15, 8
	v_writelane_b32 v252, s16, 9
	v_writelane_b32 v252, s17, 10
	v_writelane_b32 v252, s18, 11
	v_writelane_b32 v252, s19, 12
	v_writelane_b32 v252, s20, 13
	v_writelane_b32 v252, s21, 14
	v_writelane_b32 v252, s22, 15
	v_writelane_b32 v252, s23, 16
	s_cbranch_scc1 .LBB0_25
	s_cmp_lg_u32 s2, 0
	s_cbranch_scc1 .LBB0_11
	v_sub_u32_e32 v1, 0xd7f, v178
	v_lshrrev_b32_e32 v2, 9, v1
	s_add_u32 s8, s54, 0x22a2000
	v_add_u32_e32 v1, 2, v2
	v_add_u32_e32 v179, 0x200, v178
	s_mov_b32 s10, 0
	s_addc_u32 s9, s55, 0
	v_and_b32_e32 v3, 14, v1
	v_mov_b32_e32 v1, v2
	s_mov_b32 s11, 1
	s_mov_b64 s[12:13], 0
	v_mov_b32_e32 v5, 0
	s_mov_b32 s14, s10
	v_mov_b64_e32 v[6:7], v[178:179]
	s_branch .LBB0_6
